# GEMM2a covers row tiles [0,96) only; GEMM2b phase = 3 sub-passes (split rows, sample tile, full-K rows 96..127 with single RMW); packed scan
# speedup vs baseline: 1.0277x; 1.0249x over previous
; __global__ void __launch_bounds__(NWAVES * 64, 2) hybrid_fwd(Args A) {
;     ...
;             if (s == 0 && EN(1)) { pg8::Gemm g{WS_PTR(const bf16, WS_HB), WS_PTR(const bf16, WS_WINT) + (size_t)l * DINP * D, M, DINP, D, D}; pg8::StaticOrder S; S.init(M, DINP, C.G, C.bid);
;                 pg8::EpiU E{WS_PTR(bf16, WS_U), WS_PTR(const float, WS_SS) + (size_t)l * M};
;                 pg8::gemm_phase<pg8::EpiU, pg8::StaticOrder, G1_ALIGN, G1_SP2>(C.lds, g, S, E); }
;             else if (s == 1 && EN(2)) phase_prep(A, C, l);
;             else if ((s == 2 && EN(3)) || (s == 3 && EN(4)) || (s == 4 && EN(5))) {
;                 const bool split = C.G >= 192; bool go = (s == 4); int k0 = split ? KSPLIT : 0, kl = D - k0, gg = C.G, cc = C.bid, mrows = M; size_t roff = 0;
;                 if (s == 2) { go = phase_mixers(A, C, l, rep ? DUP_UN : 7); k0 = 0; kl = KSPLIT; gg = C.G - 128; cc = C.bid - 128; mrows = MP; }
;                 if (s == 3) { phase_post(A, C, l, split ? 8 : 0); go = split && C.bid < 8 && !rep; k0 = 0; kl = KSPLIT; gg = 8; cc = C.bid; mrows = MS; roff = (size_t)MP * D; }
;                 if (go) { pg8::Gemm g{WS_PTR(const bf16, WS_XN) + roff + k0, WS_PTR(const bf16, WS_WOUTT) + (size_t)l * D * D + k0, mrows, D, kl, D}; pg8::StaticOrder S; S.init(mrows, D, gg, cc);
;                     const bool first = (l == 0) && (s != 4 || !split);
;                     float* Hout = ((rep && s == 4) ? WS_PTR(float, WS_U) : A.out) + roff;
;                     pg8::EpiResN E{Hout, first ? (s == 3 ? A.in[I_XS] : A.in[I_XP]) : Hout, first ? A.in[I_XS] - (size_t)MP * D : Hout, WS_PTR(bf16, WS_HB), WS_PTR(float, WS_SS) + (size_t)(l + 1) * M, s == 4 && !rep};
;                     pg8::gemm_phase<pg8::EpiResN, pg8::StaticOrder, G2_ALIGN, true>(C.lds, g, S, E); }
.LBB0_14:
	v_readlane_b32 s12, v253, 0
	s_cmpk_lt_i32 s12, 0xb16
	s_cselect_b64 s[2:3], -1, 0
	v_writelane_b32 v253, s2, 11
	s_load_dword s13, s[0:1], 0xe8
	s_load_dwordx4 s[16:19], s[0:1], 0xc0
	s_load_dwordx2 s[14:15], s[0:1], 0xd0
	v_writelane_b32 v253, s3, 12
	s_ashr_i32 s2, s12, 31
	v_writelane_b32 v253, s2, 13
	s_lshr_b32 s2, s2, 29
	s_add_i32 s2, s12, s2
	s_ashr_i32 s9, s2, 3
	s_and_b32 s2, s2, -8
	s_sub_i32 s10, s12, s2
	s_mul_i32 s2, s10, 0x162
	s_add_i32 s11, s2, 6
	s_waitcnt lgkmcnt(0)
	s_ashr_i32 s2, s13, 31
	s_cmpk_lt_i32 s13, 0xc0
	v_writelane_b32 v253, s2, 14
	s_cselect_b64 s[2:3], -1, 0
	v_writelane_b32 v253, s2, 15
	s_cmpk_gt_i32 s13, 0xbf
	s_load_dwordx16 s[80:95], s[0:1], 0x0
	v_writelane_b32 v253, s3, 16
	s_cselect_b64 s[2:3], -1, 0
	s_and_b64 s[6:7], s[2:3], exec
	s_cselect_b32 s7, 8, 0
	s_cselect_b32 s6, 0x500, 0
	v_writelane_b32 v253, s7, 17
	v_writelane_b32 v253, s6, 18
	s_sub_i32 s6, 0x800, s6
	v_writelane_b32 v253, s6, 19
	s_add_u32 s6, s18, 0x10692000
	v_writelane_b32 v253, s6, 20
	s_addc_u32 s6, s19, 0
	v_writelane_b32 v253, s6, 21
	s_add_u32 s6, s18, 0x10200000
	v_writelane_b32 v253, s6, 22
	s_addc_u32 s6, s19, 0
	v_writelane_b32 v253, s6, 23
	s_add_u32 s6, s18, 0x10bb6000
	v_writelane_b32 v253, s6, 24
	s_addc_u32 s6, s19, 0
	v_writelane_b32 v253, s6, 25
	s_add_u32 s6, s18, 0x10492000
	v_writelane_b32 v253, s6, 26
	s_addc_u32 s6, s19, 0
	s_waitcnt lgkmcnt(0)
	s_cmp_eq_u64 s[92:93], 0
	v_writelane_b32 v253, s6, 27
	s_cselect_b64 s[6:7], -1, 0
	v_writelane_b32 v253, s6, 28
	s_cmp_lg_u64 s[92:93], 0
	s_load_dwordx16 s[36:51], s[0:1], 0x40
	v_writelane_b32 v253, s7, 29
	s_cselect_b64 s[6:7], -1, 0
	v_writelane_b32 v253, s6, 30
	v_mov_b32_e32 v207, 0x260
	v_mov_b32_e32 v229, 0x3727c5ac
	v_writelane_b32 v253, s7, 31
	s_add_u32 s6, s14, 0x8000
	v_writelane_b32 v253, s6, 32
	s_addc_u32 s6, s15, 0
	v_writelane_b32 v253, s6, 33
	s_add_i32 s6, s13, 0xffffff80
	v_writelane_b32 v253, s6, 34
	s_add_i32 s6, s12, 0xffffff80
	s_cmp_lt_i32 s12, 8
	v_writelane_b32 v253, s6, 35
	s_cselect_b64 s[6:7], -1, 0
	s_and_b64 s[2:3], s[6:7], s[2:3]
	v_writelane_b32 v253, s2, 36
	v_mov_b32_e32 v252, 1
	v_mov_b32_e32 v251, 0x7f800000
	v_writelane_b32 v253, s3, 37
	s_add_u32 s2, s82, 0xf0000000
	v_writelane_b32 v253, s2, 38
	s_addc_u32 s2, s83, -1
	s_cmp_lg_u64 s[94:95], 0
	v_writelane_b32 v253, s2, 39
	s_cselect_b64 s[2:3], -1, 0
	v_writelane_b32 v253, s2, 40
	s_cmp_lg_u32 s26, 2
	v_mov_b32_e32 v142, 0x41b17218
	v_writelane_b32 v253, s3, 41
	s_cselect_b64 s[2:3], -1, 0
	v_writelane_b32 v253, s2, 42
	v_mov_b32_e32 v143, 0x3000
	s_movk_i32 s33, 0x7fff
	v_writelane_b32 v253, s3, 43
	s_add_u32 s2, s14, 0x4200
	s_addc_u32 s3, s15, 0
	v_writelane_b32 v253, s2, 44
	s_mov_b32 s96, 0xffff0000
	s_mov_b32 s97, 0x3fb8aa3b
	v_writelane_b32 v253, s3, 45
	s_add_u32 s2, s14, 0x4400
	s_addc_u32 s3, s15, 0
	v_writelane_b32 v253, s2, 46
	s_mov_b32 s20, 0xbfb8aa3b
	s_mov_b32 s21, 0xb2a5705f
	v_writelane_b32 v253, s3, 47
	s_add_u32 s2, s14, 0x4500
	s_addc_u32 s3, s15, 0
	v_writelane_b32 v253, s2, 48
	s_mov_b32 s28, 0x42ce8ed0
	s_mov_b32 s29, 0xc2b17218
	v_writelane_b32 v253, s3, 49
	s_add_u32 s2, s14, 0x4600
	s_addc_u32 s3, s15, 0
	v_writelane_b32 v253, s2, 50
	s_mov_b32 s34, 0x7f800000
	s_mov_b32 s35, 0x800000
	v_writelane_b32 v253, s3, 51
	s_add_u32 s2, s14, 0x4700
	s_addc_u32 s3, s15, 0
	v_writelane_b32 v253, s2, 52
	s_mov_b64 s[22:23], 0x80
	s_nop 0
	v_writelane_b32 v253, s3, 53
	s_add_u32 s2, s14, 0x4800
	s_addc_u32 s3, s15, 0
	v_writelane_b32 v253, s2, 54
	s_nop 1
	v_writelane_b32 v253, s3, 55
	s_add_u32 s2, s14, 0x4900
	s_addc_u32 s3, s15, 0
	v_writelane_b32 v253, s2, 56
	s_nop 1
	v_writelane_b32 v253, s3, 57
	s_add_u32 s2, s14, 0x4a00
	s_addc_u32 s3, s15, 0
	v_writelane_b32 v253, s2, 58
	s_nop 1
	v_writelane_b32 v253, s3, 59
	s_add_u32 s2, s14, 0x4b00
	s_addc_u32 s3, s15, 0
	v_writelane_b32 v253, s2, 60
	s_nop 1
	v_writelane_b32 v253, s3, 61
	s_add_u32 s2, s14, 0x4c00
	s_addc_u32 s3, s15, 0
	v_writelane_b32 v253, s2, 62
	s_nop 1
	v_writelane_b32 v253, s3, 63
	s_add_u32 s2, s14, 0x4d00
	s_addc_u32 s3, s15, 0
	v_writelane_b32 v254, s2, 0
	s_nop 1
	v_writelane_b32 v254, s3, 1
	s_add_u32 s2, s14, 0x4e00
	s_addc_u32 s3, s15, 0
	v_writelane_b32 v254, s2, 2
	s_nop 1
	v_writelane_b32 v254, s3, 3
	s_add_u32 s2, s14, 0x4f00
	s_addc_u32 s3, s15, 0
	v_writelane_b32 v254, s2, 4
	s_nop 1
	v_writelane_b32 v254, s3, 5
	s_add_u32 s2, s14, 0x5000
	s_addc_u32 s3, s15, 0
	v_writelane_b32 v254, s2, 6
	s_nop 1
	v_writelane_b32 v254, s3, 7
	s_add_u32 s2, s14, 0x5100
	s_addc_u32 s3, s15, 0
	v_writelane_b32 v254, s2, 8
	s_nop 1
	v_writelane_b32 v254, s3, 9
	s_add_u32 s2, s14, 0x5200
	s_addc_u32 s3, s15, 0
	v_writelane_b32 v254, s2, 10
	s_nop 1
	v_writelane_b32 v254, s3, 11
	s_add_u32 s2, s14, 0x5300
	s_addc_u32 s3, s15, 0
	v_writelane_b32 v254, s2, 12
	s_cmp_eq_u32 s8, 15
	s_nop 0
	v_writelane_b32 v254, s3, 13
	s_cselect_b64 s[2:3], -1, 0
	v_writelane_b32 v254, s2, 14
	s_cmp_eq_u32 s8, 14
	s_nop 0
	v_writelane_b32 v254, s3, 15
	s_cselect_b64 s[2:3], -1, 0
	v_writelane_b32 v254, s2, 16
	s_cmp_eq_u32 s8, 13
	s_nop 0
	v_writelane_b32 v254, s3, 17
	s_cselect_b64 s[2:3], -1, 0
	v_writelane_b32 v254, s2, 18
; __device__ __forceinline__ unsigned xb_ld(unsigned* p)              { return __hip_atomic_load(p, __ATOMIC_RELAXED, __HIP_MEMORY_SCOPE_AGENT); }
;     __host__ __device__ bool next(int i, Unit& u) const {
;         const long L = (long)i * G + c; if (L >= nwg) return false;
;         int wgid = (int)L; { const int q = nwg / NXCD, r = nwg % NXCD, xcd = wgid % NXCD, off = wgid / NXCD; wgid = (xcd < r ? xcd * (q + 1) : r * (q + 1) + (xcd - r) * q) + off; }
;         const int nig = WGM * nN, gid = wgid / nig, fm = gid * WGM, gsz = (nM - fm) < WGM ? (nM - fm) : WGM;
;         u.pm = fm + ((wgid % nig) % gsz); u.pn = (wgid % nig) / gsz; return true;
; __device__ __forceinline__ void xcd_barrier_complete(unsigned* bar, unsigned x, unsigned& nloc, unsigned& nx) {
;     const unsigned G = gridDim.x * gridDim.y * gridDim.z;
;     unsigned sum, cnt, mine, sp = 0u;
;     for (;;) {
;         sum = 0u; cnt = 0u; mine = 0u;
; #pragma unroll
;         for (unsigned j = 0; j < 16; ++j) { const unsigned c = xb_ld(&bar[XB_XCNT(j)]); sum += c; cnt += (c > 0u) ? 1u : 0u; mine = (j == x) ? c : mine; }
;         if (sum == G) break;
;         __builtin_amdgcn_s_sleep(1);
;         if ((++sp & 255u) == 0u) { if (xb_ld(&bar[XB_TMO])) break; if (sp > XB_SPIN_CAP) { atomicAdd(&bar[XB_TMO], 1u); break; } }
;     }
;     nloc = mine > 0u ? mine : 1u; nx = cnt > 0u ? cnt : 1u;
	s_cmp_eq_u32 s8, 12
	s_nop 0
	v_writelane_b32 v254, s3, 19
	s_cselect_b64 s[2:3], -1, 0
	v_writelane_b32 v254, s2, 20
	s_cmp_eq_u32 s8, 11
	s_nop 0
	v_writelane_b32 v254, s3, 21
	s_cselect_b64 s[2:3], -1, 0
	v_writelane_b32 v254, s2, 22
	s_cmp_eq_u32 s8, 10
	s_nop 0
	v_writelane_b32 v254, s3, 23
	s_cselect_b64 s[2:3], -1, 0
	v_writelane_b32 v254, s2, 24
	s_cmp_eq_u32 s8, 9
	s_nop 0
	v_writelane_b32 v254, s3, 25
	s_cselect_b64 s[2:3], -1, 0
	v_writelane_b32 v254, s2, 26
	s_cmp_eq_u32 s8, 8
	s_nop 0
	v_writelane_b32 v254, s3, 27
	s_cselect_b64 s[2:3], -1, 0
	v_writelane_b32 v254, s2, 28
	s_cmp_eq_u32 s8, 7
	s_nop 0
	v_writelane_b32 v254, s3, 29
	s_cselect_b64 s[2:3], -1, 0
	v_writelane_b32 v254, s2, 30
	s_cmp_eq_u32 s8, 6
	s_nop 0
	v_writelane_b32 v254, s3, 31
	s_cselect_b64 s[2:3], -1, 0
	v_writelane_b32 v254, s2, 32
	s_cmp_eq_u32 s8, 5
	s_nop 0
	v_writelane_b32 v254, s3, 33
	s_cselect_b64 s[2:3], -1, 0
	v_writelane_b32 v254, s2, 34
	s_cmp_eq_u32 s8, 4
	s_nop 0
	v_writelane_b32 v254, s3, 35
	s_cselect_b64 s[2:3], -1, 0
	v_writelane_b32 v254, s2, 36
	s_cmp_eq_u32 s8, 3
	s_nop 0
	v_writelane_b32 v254, s3, 37
	s_cselect_b64 s[2:3], -1, 0
	v_writelane_b32 v254, s2, 38
	s_cmp_eq_u32 s8, 2
	s_nop 0
	v_writelane_b32 v254, s3, 39
	s_cselect_b64 s[2:3], -1, 0
	v_writelane_b32 v254, s2, 40
	s_cmp_eq_u32 s8, 1
	s_nop 0
	v_writelane_b32 v254, s3, 41
	s_cselect_b64 s[2:3], -1, 0
	v_writelane_b32 v254, s2, 42
	s_cmp_eq_u32 s8, 0
	s_nop 0
	v_writelane_b32 v254, s3, 43
	s_cselect_b64 s[2:3], -1, 0
	v_writelane_b32 v254, s2, 44
	s_nop 1
	v_writelane_b32 v254, s3, 45
	s_lshl_b32 s2, s8, 8
	s_add_u32 s2, s4, s2
	s_addc_u32 s3, s5, 0
	s_add_u32 s4, s2, 0x1400
	s_addc_u32 s5, s3, 0
	v_writelane_b32 v254, s4, 46
	s_add_u32 s2, s2, 0x2400
	s_addc_u32 s3, s3, 0
	v_writelane_b32 v254, s5, 47
	v_writelane_b32 v254, s2, 48
	s_nop 1
	v_writelane_b32 v254, s3, 49
	s_add_u32 s2, s14, 0x7400
	s_addc_u32 s3, s15, 0
	v_writelane_b32 v254, s2, 50
	s_nop 1
	v_writelane_b32 v254, s3, 51
	s_add_u32 s2, s14, 0x7500
	s_addc_u32 s3, s15, 0
	v_writelane_b32 v254, s2, 52
	s_cmp_lt_i32 s10, 6
	s_mulk_i32 s10, 0x163
	v_writelane_b32 v254, s3, 53
	s_cselect_b32 s2, s10, s11
	s_add_i32 s2, s2, s9
	s_mul_hi_i32 s3, s2, 0x2e8ba2e9
	s_lshr_b32 s4, s3, 31
	s_ashr_i32 s3, s3, 5
	s_add_i32 s3, s3, s4
	s_mul_i32 s4, s3, 0xb0
	s_lshl_b32 s5, s3, 3
	s_sub_i32 s4, s2, s4
	s_sub_i32 s2, 0x81, s5
	s_min_u32 s6, s2, 8
	v_cvt_f32_ubyte0_e32 v2, s6
	v_cvt_f32_i32_e32 v1, s4
	v_rcp_iflag_f32_e32 v3, v2
	s_ashr_i32 s2, s4, 30
	s_or_b32 s7, s2, 1
	v_mul_f32_e32 v3, v1, v3
	v_trunc_f32_e32 v3, v3
	v_fma_f32 v1, -v3, v2, v1
	v_cmp_ge_f32_e64 s[2:3], |v1|, v2
	v_lshrrev_b32_e32 v1, 20, v0
	v_lshrrev_b32_e32 v0, 10, v0
	v_or_b32_e32 v0, v0, v1
	v_cvt_i32_f32_e32 v1, v3
	s_and_b64 s[2:3], s[2:3], exec
	s_movk_i32 s2, 0x3ff
	v_and_or_b32 v0, v0, s2, v185
	s_cselect_b32 s2, s7, 0
	v_readfirstlane_b32 s3, v1
	s_add_i32 s2, s3, s2
	s_mul_i32 s3, s2, s6
	s_sub_i32 s3, s4, s3
	s_sext_i32_i16 s3, s3
	s_add_i32 s3, s5, s3
	v_writelane_b32 v254, s3, 54
	s_sext_i32_i16 s2, s2
	v_writelane_b32 v254, s2, 55
	s_add_u32 s2, s14, 0xfc54300
	s_addc_u32 s3, s15, 0
	v_writelane_b32 v254, s2, 56
	v_mov_b32_e32 v1, 0
	v_mov_b32_e32 v98, v1
	v_writelane_b32 v254, s3, 57
	s_add_u32 s2, s14, 0xfc3c000
	v_writelane_b32 v254, s2, 58
	s_addc_u32 s2, s15, 0
	v_writelane_b32 v254, s2, 59
	s_add_i32 s2, 0, 0xd000
	v_writelane_b32 v254, s2, 60
	s_add_i32 s2, 0, 0x3cf0
	v_writelane_b32 v254, s2, 61
	s_mov_b32 s3, 0
	v_writelane_b32 v254, s2, 62
	v_mov_b32_e32 v99, v1
	v_mov_b32_e32 v100, v1
	v_writelane_b32 v254, s3, 63
	v_cmp_eq_u32_e64 s[2:3], 0, v185
	v_mov_b32_e32 v101, v1
	s_mov_b32 s4, 0x3f317217
	v_writelane_b32 v255, s2, 0
	s_mov_b32 s5, 0xc2ce8ed0
	s_mov_b32 s6, 0x42b17218
	v_writelane_b32 v255, s3, 1
	v_cmp_eq_u32_e64 s[2:3], 0, v0
	s_mov_b32 s7, 0xf800000
	s_nop 0
	v_writelane_b32 v255, s2, 2
	s_nop 1
	v_writelane_b32 v255, s3, 3
	s_waitcnt lgkmcnt(0)
	v_writelane_b32 v255, s36, 4
	s_nop 1
	v_writelane_b32 v255, s37, 5
	v_writelane_b32 v255, s38, 6
	v_writelane_b32 v255, s39, 7
	v_writelane_b32 v255, s40, 8
	v_writelane_b32 v255, s41, 9
	v_writelane_b32 v255, s42, 10
	v_writelane_b32 v255, s43, 11
	v_writelane_b32 v255, s44, 12
	v_writelane_b32 v255, s45, 13
	v_writelane_b32 v255, s46, 14
	v_writelane_b32 v255, s47, 15
	v_writelane_b32 v255, s48, 16
	v_writelane_b32 v255, s49, 17
	v_writelane_b32 v255, s50, 18
	v_writelane_b32 v255, s51, 19
	s_load_dwordx16 s[36:51], s[0:1], 0x80
	s_waitcnt lgkmcnt(0)
	v_writelane_b32 v255, s36, 20
	s_nop 1
	v_writelane_b32 v255, s37, 21
	v_writelane_b32 v255, s38, 22
	v_writelane_b32 v255, s39, 23
	v_writelane_b32 v255, s40, 24
	v_writelane_b32 v255, s41, 25
	v_writelane_b32 v255, s42, 26
	v_writelane_b32 v255, s43, 27
	v_writelane_b32 v255, s44, 28
	v_writelane_b32 v255, s45, 29
	v_writelane_b32 v255, s46, 30
	v_writelane_b32 v255, s47, 31
	v_writelane_b32 v255, s48, 32
	v_writelane_b32 v255, s49, 33
	v_writelane_b32 v255, s50, 34
	v_writelane_b32 v255, s51, 35
	s_mov_b32 s98, 0
	v_writelane_b32 v255, s98, 61
	v_writelane_b32 v255, s98, 62
	v_writelane_b32 v255, s98, 63
	s_branch .LBB0_19

; __global__ void __launch_bounds__(NWAVES * 64, 2) hybrid_fwd(Args A) {
;     ...
;             else if ((s == 2 && EN(3)) || (s == 3 && EN(4)) || (s == 4 && EN(5))) {
;                 const bool split = C.G >= 192; bool go = (s == 4); int k0 = split ? KSPLIT : 0, kl = D - k0, gg = C.G, cc = C.bid, mrows = M; size_t roff = 0;
;                 if (s == 2) { go = phase_mixers(A, C, l, rep ? DUP_UN : 7); k0 = 0; kl = KSPLIT; gg = C.G - 128; cc = C.bid - 128; mrows = MP; }
;                 if (s == 3) { phase_post(A, C, l, split ? 8 : 0); go = split && C.bid < 8 && !rep; k0 = 0; kl = KSPLIT; gg = 8; cc = C.bid; mrows = MS; roff = (size_t)MP * D; }
;                 if (go) { pg8::Gemm g{WS_PTR(const bf16, WS_XN) + roff + k0, WS_PTR(const bf16, WS_WOUTT) + (size_t)l * D * D + k0, mrows, D, kl, D}; pg8::StaticOrder S; S.init(mrows, D, gg, cc);
;                     const bool first = (l == 0) && (s != 4 || !split);
;                     float* Hout = ((rep && s == 4) ? WS_PTR(float, WS_U) : A.out) + roff;
;                     pg8::EpiResN E{Hout, first ? (s == 3 ? A.in[I_XS] : A.in[I_XP]) : Hout, first ? A.in[I_XS] - (size_t)MP * D : Hout, WS_PTR(bf16, WS_HB), WS_PTR(float, WS_SS) + (size_t)(l + 1) * M, s == 4 && !rep};
;                     pg8::gemm_phase<pg8::EpiResN, pg8::StaticOrder, G2_ALIGN, true>(C.lds, g, S, E); }
.LBB0_675:
	s_movk_i32 s11, 0x60
	s_mov_b32 s98, 0
	v_writelane_b32 v255, s98, 61
	v_writelane_b32 v255, s98, 62
	v_writelane_b32 v255, s98, 63
	v_readlane_b32 s30, v253, 0
	v_readlane_b32 s17, v253, 3
	v_readlane_b32 s3, v253, 19
	v_readlane_b32 s8, v253, 18
	s_branch .LBB0_1183

; __global__ void __launch_bounds__(NWAVES * 64, 2) hybrid_fwd(Args A) {
;     ...
;                 if (s == 2) { go = phase_mixers(A, C, l, rep ? DUP_UN : 7); k0 = 0; kl = KSPLIT; gg = C.G - 128; cc = C.bid - 128; mrows = MP; }
;                 if (s == 3) { phase_post(A, C, l, split ? 8 : 0); go = split && C.bid < 8 && !rep; k0 = 0; kl = KSPLIT; gg = 8; cc = C.bid; mrows = MS; roff = (size_t)MP * D; }
;                 if (go) { pg8::Gemm g{WS_PTR(const bf16, WS_XN) + roff + k0, WS_PTR(const bf16, WS_WOUTT) + (size_t)l * D * D + k0, mrows, D, kl, D}; pg8::StaticOrder S; S.init(mrows, D, gg, cc);
.LBB0_1181:
.LBB0_1182:
	s_mov_b32 s8, 0
	s_movk_i32 s3, 0x500
	s_movk_i32 s11, 0x60
	v_readlane_b32 s30, v253, 35
	v_readlane_b32 s17, v253, 34

; #define PG8_STAGE(bufoff, gbase, voff) do { _Pragma("unroll") for (int _i = 0; _i < 2; ++_i) \
;         __builtin_amdgcn_global_load_lds((const unsigned*)((const char*)(gbase) + (voff)[_i]), (PG8_LAS unsigned*)(lds + (bufoff) + ldsw + _i * 8192), 16, 0, 0); } while (0)
; #define PG8_WAIT_V(n) asm volatile("s_waitcnt vmcnt(" #n ")" ::: "memory")
; #define PG8_BAR __builtin_amdgcn_s_barrier()
; template <class Epi, class Sched, bool ALIGN_EPI = false, bool SP2 = false>
; __device__ __forceinline__ void gemm_phase(PG8_LAS unsigned char* lds, const Gemm g, const Sched& S, const Epi& E) {
;     ...
;         PG8_STAGE(PG8_SB(0, 0), cB, voffB); PG8_STAGE(PG8_SB(0, 1), cB + hstep, voffB); PG8_STAGE(PG8_SA(0, 0), cA, voffA); PG8_STAGE(PG8_SA(0, 1), cA + hstep, voffA);
;         if (wr == 1) PG8_BAR;
;         PG8_WAIT_V(2); PG8_BAR;
;         PG8_STAGE(PG8_SB(1, 0), cB + kstep, voffB); PG8_STAGE(PG8_SA(1, 0), cA + kstep, voffA); PG8_STAGE(PG8_SB(1, 1), cB + hstep + kstep, voffB);
;         PG8_WAIT_V(6); PG8_BAR;
;     } else {
;         PG8_STAGE(PG8_SB(0, 0), cB, voffB); PG8_STAGE(PG8_SA(0, 0), cA, voffA); PG8_STAGE(PG8_SB(0, 1), cB + hstep, voffB); PG8_STAGE(PG8_SA(0, 1), cA + hstep, voffA);
;         if (wr == 1) PG8_BAR;
;         PG8_WAIT_V(4); PG8_BAR;
;         PG8_STAGE(PG8_SB(1, 0), cB + kstep, voffB); PG8_STAGE(PG8_SA(1, 0), cA + kstep, voffA); PG8_STAGE(PG8_SB(1, 1), cB + hstep + kstep, voffB);
;         PG8_WAIT_V(6); PG8_BAR;
; __global__ void __launch_bounds__(NWAVES * 64, 2) hybrid_fwd(Args A) {
;     ...
;                 if (go) { pg8::Gemm g{WS_PTR(const bf16, WS_XN) + roff + k0, WS_PTR(const bf16, WS_WOUTT) + (size_t)l * D * D + k0, mrows, D, kl, D}; pg8::StaticOrder S; S.init(mrows, D, gg, cc);
;                     const bool first = (l == 0) && (s != 4 || !split);
;                     float* Hout = ((rep && s == 4) ? WS_PTR(float, WS_U) : A.out) + roff;
;                     pg8::EpiResN E{Hout, first ? (s == 3 ? A.in[I_XS] : A.in[I_XP]) : Hout, first ? A.in[I_XS] - (size_t)MP * D : Hout, WS_PTR(bf16, WS_HB), WS_PTR(float, WS_SS) + (size_t)(l + 1) * M, s == 4 && !rep};
.LBB0_1195:
	v_readlane_b32 s12, v255, 36
	s_add_i32 s10, s12, 4
	v_readlane_b32 s13, v255, 37
	s_cmp_lt_u32 s10, 11
	v_readlane_b32 s10, v255, 53
	v_readlane_b32 s14, v255, 38
	v_readlane_b32 s15, v255, 39
	s_cselect_b64 s[12:13], -1, 0
	s_cmp_lg_u32 s10, 4
	v_readlane_b32 s18, v253, 15
	s_cselect_b64 s[14:15], -1, 0
	v_readlane_b32 s19, v253, 16
	s_or_b64 s[14:15], s[14:15], s[18:19]
	v_readlane_b32 s18, v255, 62
	s_cmp_lg_u32 s18, 0
	s_cselect_b64 s[18:19], -1, 0
	s_or_b64 s[14:15], s[14:15], s[18:19]
	s_and_b64 s[12:13], s[12:13], s[14:15]
	s_and_b64 s[14:15], s[38:39], exec
	s_cselect_b32 s10, s82, s80
	s_cselect_b32 s14, s83, s81
	s_lshl_b32 s15, s40, 2
	v_readlane_b32 s18, v255, 62
	s_cmp_lg_u32 s18, 0
	s_cselect_b32 s18, s15, 0
	s_add_u32 s10, s10, s18
	s_addc_u32 s14, s14, 0
	v_readlane_b32 s40, v253, 6
	v_readlane_b32 s42, v253, 8
	v_readlane_b32 s43, v253, 9
	s_add_u32 s42, s42, s15
	s_addc_u32 s43, s43, 0
	s_and_b64 s[12:13], s[12:13], exec
	v_bfe_u32 v17, v16, 4, 2
	s_cselect_b32 s71, s10, s42
	v_readlane_b32 s10, v253, 39
	v_and_b32_e32 v16, 15, v16
	v_lshlrev_b32_e32 v18, 4, v17
	s_cselect_b32 s72, s10, s43
	v_readlane_b32 s10, v253, 38
	v_lshl_or_b32 v156, s8, 6, v16
	v_lshl_or_b32 v18, v16, 6, v18
	v_lshlrev_b32_e32 v16, 2, v16
	s_cselect_b32 s13, s14, s43
	s_cselect_b32 s73, s10, s42
	s_lshr_b32 s74, s3, 6
	s_lshl_b32 s3, s8, 13
	v_and_b32_e32 v19, 32, v16
	v_bitop3_b32 v20, v18, s3, v19 bitop3:0xde
	s_lshl_b32 s3, s9, 5
	s_and_b32 s3, s3, 0x60
	s_lshl_b32 s8, s3, 7
	v_bitop3_b32 v157, v18, s8, v19 bitop3:0xde
	v_readlane_b32 s8, v255, 44
	v_readlane_b32 s9, v255, 45
	s_add_i32 s8, s8, 1
	s_mul_hi_i32 s9, s8, 0x20400
	s_mul_i32 s8, s8, 0x20400
	v_readlane_b32 s10, v255, 49
	s_add_u32 s44, s10, s8
	v_readlane_b32 s8, v255, 52
	s_addc_u32 s45, s8, s9
	s_add_i32 m0, s59, 0x18000
	v_lshl_add_u64 v[8:9], v[8:9], 0, s[22:23]
	s_waitcnt vmcnt(2)
	s_barrier
	global_load_lds_dwordx4 v[8:9], off
	v_lshl_add_u64 v[6:7], v[6:7], 0, s[22:23]
	s_add_i32 m0, s59, 0x1a000
	s_add_i32 s75, s59, 0x8000
	s_add_i32 s76, s59, 0xa000
	global_load_lds_dwordx4 v[6:7], off
	v_lshl_add_u64 v[2:3], v[2:3], 0, s[22:23]
	s_mov_b32 m0, s75
	s_add_u32 s8, s60, 0x80080
	global_load_lds_dwordx4 v[2:3], off
	v_lshl_add_u64 v[2:3], v[4:5], 0, s[22:23]
	s_mov_b32 m0, s76
	s_addc_u32 s9, s61, 0
	global_load_lds_dwordx4 v[2:3], off
	s_add_i32 m0, s59, 0x1c000
	v_lshl_add_u64 v[2:3], s[8:9], 0, v[0:1]
	global_load_lds_dwordx4 v[2:3], off
	v_lshl_add_u64 v[2:3], s[8:9], 0, v[138:139]
	s_add_i32 m0, s59, 0x1e000
	s_add_i32 s77, s74, -2
	global_load_lds_dwordx4 v[2:3], off
	s_cmpk_lt_u32 s2, 0x100
	v_lshlrev_b32_e32 v2, 6, v17
	s_movk_i32 s2, 0x80
	v_bitop3_b32 v158, v2, 64, v16 bitop3:0x36
	v_bitop3_b32 v159, v2, s2, v16 bitop3:0x36
	v_lshlrev_b32_e32 v2, 15, v13
	v_and_b32_e32 v2, 0xffff0000, v2
	v_lshl_add_u32 v2, v14, 12, v2
	v_and_b32_e32 v3, 1, v13
	v_lshl_or_b32 v2, v3, 6, v2
	v_lshl_add_u32 v140, v15, 1, v2
	v_lshlrev_b32_e32 v2, 15, v10
	v_and_b32_e32 v2, 0xffff0000, v2
	s_waitcnt vmcnt(6)
	v_lshl_add_u32 v2, v11, 12, v2
	v_and_b32_e32 v3, 1, v10
	v_lshl_or_b32 v2, v3, 6, v2
	s_cselect_b64 s[46:47], -1, 0
	s_mov_b32 s78, 0
	v_cmp_eq_u32_e64 s[38:39], 0, v17
	s_ashr_i32 s79, s17, 31
	s_ashr_i32 s10, s30, 31
	v_lshl_or_b32 v160, v17, 3, s3
	v_mov_b32_e32 v141, v1
	v_lshl_add_u32 v144, v12, 1, v2
	v_mov_b32_e32 v145, v1
	v_add_u32_e32 v161, 0, v20
	v_readlane_b32 s41, v253, 7
	s_barrier
	s_branch .LBB0_1198

; __device__ __forceinline__ unsigned cvt_pk_bf16(float lo, float hi) { unsigned r; asm volatile("v_cvt_pk_bf16_f32 %0, %1, %2" : "=v"(r) : "v"(lo), "v"(hi)); return r; }
;     __device__ __forceinline__ void operator()(const f32x4 (&acc)[2][2][4][2], const Unit& u, int wr, int wc, int fr, int fq) const {
;         const int col0 = u.pn * BM + wc * 32 + 8 * fq;
; #pragma unroll
;         for (int ai = 0; ai < 2; ++ai)
; #pragma unroll
;             for (int m = 0; m < 4; ++m) { const int row = u.pm * BM + ai * HALF + wr * 64 + m * 16 + fr; float* rowp = H + (size_t)row * 2048 + col0; bf16_t* hbp = HB + (size_t)row * 2048 + col0;
;                 const float* inp = (u.pm < 128 ? HinP : HinS) + (size_t)row * 2048 + col0;
;                 float ss = 0.f;
; #pragma unroll
;                 for (int bj = 0; bj < 2; ++bj) { const f32x4 h0 = *(const f32x4*)(inp + bj * HALF) + acc[ai][bj][m][0], h1 = *(const f32x4*)(inp + bj * HALF + 4) + acc[ai][bj][m][1];
;                     *(f32x4*)(rowp + bj * HALF) = h0; *(f32x4*)(rowp + bj * HALF + 4) = h1;
;                     if (fin) { ss += ((h0[0] * h0[0] + h0[1] * h0[1]) + (h0[2] * h0[2] + h0[3] * h0[3])) + ((h1[0] * h1[0] + h1[1] * h1[1]) + (h1[2] * h1[2] + h1[3] * h1[3]));
;                         u32x4 w; w.x = cvt_pk_bf16(h0[0], h0[1]); w.y = cvt_pk_bf16(h0[2], h0[3]); w.z = cvt_pk_bf16(h1[0], h1[1]); w.w = cvt_pk_bf16(h1[2], h1[3]);
;                         *(u32x4*)(hbp + bj * HALF) = w; } }
;                 if (fin) { { const int ln = fr + 16 * fq; ss += __int_as_float(__builtin_amdgcn_ds_bpermute((ln ^ 16) << 2, __float_as_int(ss))); ss += __int_as_float(__builtin_amdgcn_ds_bpermute((ln ^ 32) << 2, __float_as_int(ss))); }
;                     if (fq == 0) atomicAdd(SSn + row, ss); } }
.LBB0_1204:
	v_lshl_add_u32 v146, s58, 8, v156
	v_lshl_or_b32 v148, s24, 8, v160
	s_cmpk_lt_i32 s58, 0x80
	v_ashrrev_i32_e32 v147, 31, v146
	v_ashrrev_i32_e32 v149, 31, v148
	v_lshlrev_b64 v[152:153], 13, v[146:147]
	s_cselect_b32 s25, s13, s72
	s_cselect_b32 s24, s71, s73
	v_lshlrev_b64 v[150:151], 2, v[148:149]
	v_lshl_add_u64 v[154:155], s[24:25], 0, v[152:153]
	v_lshl_add_u64 v[154:155], v[154:155], 0, v[150:151]
	v_readlane_b32 s8, v255, 54
	v_readlane_b32 s9, v255, 55
	v_lshl_add_u64 v[152:153], s[42:43], 0, v[152:153]
	s_and_b64 vcc, exec, s[8:9]
	v_lshl_add_u64 v[152:153], v[152:153], 0, v[150:151]
	s_mov_b64 s[2:3], 0x20000
	s_mov_b64 s[8:9], 0xa0000
	s_cbranch_vccnz .Lmy_epi_nofin
	v_readlane_b32 s24, v255, 47
	v_readlane_b32 s25, v255, 48
	v_readlane_b32 s98, v255, 63
	s_nop 1
	v_add_u32_e32 v204, s98, v146
	v_mov_b32_e32 v205, 0
	v_lshlrev_b64 v[162:163], 11, v[204:205]
	v_lshl_add_u64 v[186:187], v[204:205], 2, s[44:45]
	s_nop 1
	v_lshl_add_u64 v[162:163], v[162:163], 1, s[24:25]
	v_lshl_add_u64 v[162:163], v[148:149], 1, v[162:163]
	s_mov_b64 s[98:99], 0x10000
	s_mov_b64 s[24:25], 0x50000
	global_load_dwordx4 v[164:167], v[154:155], off
	global_load_dwordx4 v[168:171], v[154:155], off offset:16
	global_load_dwordx4 v[172:175], v[154:155], off offset:512
	global_load_dwordx4 v[176:179], v[154:155], off offset:528
	v_lshl_add_u64 v[154:155], v[154:155], 0, s[2:3]
	global_load_dwordx4 v[180:183], v[154:155], off
	global_load_dwordx4 v[188:191], v[154:155], off offset:16
	global_load_dwordx4 v[192:195], v[154:155], off offset:512
	global_load_dwordx4 v[196:199], v[154:155], off offset:528
	v_lshl_add_u64 v[154:155], v[154:155], 0, s[2:3]
	global_load_dwordx4 v[200:203], v[154:155], off
	global_load_dwordx4 v[208:211], v[154:155], off offset:16
	global_load_dwordx4 v[212:215], v[154:155], off offset:512
	global_load_dwordx4 v[216:219], v[154:155], off offset:528
	v_lshl_add_u64 v[154:155], v[154:155], 0, s[2:3]
	global_load_dwordx4 v[220:223], v[154:155], off
	global_load_dwordx4 v[224:227], v[154:155], off offset:16
	global_load_dwordx4 v[232:235], v[154:155], off offset:512
	global_load_dwordx4 v[236:239], v[154:155], off offset:528
	v_lshl_add_u64 v[154:155], v[154:155], 0, s[8:9]
	s_waitcnt vmcnt(12)
	v_pk_add_f32 v[130:131], v[130:131], v[164:165]
	v_pk_add_f32 v[132:133], v[132:133], v[166:167]
	v_pk_add_f32 v[126:127], v[126:127], v[168:169]
	v_pk_add_f32 v[128:129], v[128:129], v[170:171]
	v_pk_add_f32 v[122:123], v[122:123], v[172:173]
	v_pk_add_f32 v[124:125], v[124:125], v[174:175]
	v_pk_add_f32 v[118:119], v[118:119], v[176:177]
	v_pk_add_f32 v[120:121], v[120:121], v[178:179]
	global_load_dwordx4 v[164:167], v[154:155], off
	global_load_dwordx4 v[168:171], v[154:155], off offset:16
	global_load_dwordx4 v[172:175], v[154:155], off offset:512
	global_load_dwordx4 v[176:179], v[154:155], off offset:528
	v_lshl_add_u64 v[154:155], v[154:155], 0, s[2:3]
	global_store_dwordx4 v[152:153], v[130:133], off
	global_store_dwordx4 v[152:153], v[126:129], off offset:16
	global_store_dwordx4 v[152:153], v[122:125], off offset:512
	global_store_dwordx4 v[152:153], v[118:121], off offset:528
	v_lshl_add_u64 v[152:153], v[152:153], 0, s[2:3]
	v_mul_f32_e32 v248, v131, v131
	v_mul_f32_e32 v249, v133, v133
	v_fmac_f32_e32 v248, v130, v130
	v_fmac_f32_e32 v249, v132, v132
	v_add_f32_e32 v248, v248, v249
	v_mul_f32_e32 v250, v127, v127
	v_mul_f32_e32 v230, v129, v129
	v_fmac_f32_e32 v250, v126, v126
	v_fmac_f32_e32 v230, v128, v128
	v_add_f32_e32 v250, v250, v230
	v_add_f32_e32 v248, v248, v250
	v_mul_f32_e32 v231, v123, v123
	v_mul_f32_e32 v249, v125, v125
	v_fmac_f32_e32 v231, v122, v122
	v_fmac_f32_e32 v249, v124, v124
	v_add_f32_e32 v231, v231, v249
	v_mul_f32_e32 v250, v119, v119
	v_mul_f32_e32 v230, v121, v121
	v_fmac_f32_e32 v250, v118, v118
	v_fmac_f32_e32 v230, v120, v120
	v_add_f32_e32 v250, v250, v230
	v_add_f32_e32 v231, v231, v250
	v_add_f32_e32 v248, v248, v231
	ds_bpermute_b32 v230, v158, v248
	v_cvt_pk_bf16_f32 v240, v130, v131
	v_cvt_pk_bf16_f32 v241, v132, v133
	v_cvt_pk_bf16_f32 v242, v126, v127
	v_cvt_pk_bf16_f32 v243, v128, v129
	v_cvt_pk_bf16_f32 v244, v122, v123
	v_cvt_pk_bf16_f32 v245, v124, v125
	v_cvt_pk_bf16_f32 v246, v118, v119
	v_cvt_pk_bf16_f32 v247, v120, v121
	global_store_dwordx4 v[162:163], v[240:243], off
	global_store_dwordx4 v[162:163], v[244:247], off offset:256
	s_waitcnt lgkmcnt(0)
	v_add_f32_e32 v248, v248, v230
	ds_bpermute_b32 v230, v159, v248
	v_lshl_add_u64 v[162:163], v[162:163], 0, s[98:99]
	s_waitcnt lgkmcnt(0)
	v_add_f32_e32 v248, v248, v230
	s_and_saveexec_b64 vcc, s[38:39]
	global_atomic_add_f32 v[186:187], v248, off
	s_mov_b64 exec, vcc
	s_waitcnt vmcnt(19)
; __device__ __forceinline__ unsigned cvt_pk_bf16(float lo, float hi) { unsigned r; asm volatile("v_cvt_pk_bf16_f32 %0, %1, %2" : "=v"(r) : "v"(lo), "v"(hi)); return r; }
;     __device__ __forceinline__ void operator()(const f32x4 (&acc)[2][2][4][2], const Unit& u, int wr, int wc, int fr, int fq) const {
;     ...
;         for (int ai = 0; ai < 2; ++ai)
; #pragma unroll
;             for (int m = 0; m < 4; ++m) { const int row = u.pm * BM + ai * HALF + wr * 64 + m * 16 + fr; float* rowp = H + (size_t)row * 2048 + col0; bf16_t* hbp = HB + (size_t)row * 2048 + col0;
;                 const float* inp = (u.pm < 128 ? HinP : HinS) + (size_t)row * 2048 + col0;
;                 float ss = 0.f;
; #pragma unroll
;                 for (int bj = 0; bj < 2; ++bj) { const f32x4 h0 = *(const f32x4*)(inp + bj * HALF) + acc[ai][bj][m][0], h1 = *(const f32x4*)(inp + bj * HALF + 4) + acc[ai][bj][m][1];
;                     *(f32x4*)(rowp + bj * HALF) = h0; *(f32x4*)(rowp + bj * HALF + 4) = h1;
;                     if (fin) { ss += ((h0[0] * h0[0] + h0[1] * h0[1]) + (h0[2] * h0[2] + h0[3] * h0[3])) + ((h1[0] * h1[0] + h1[1] * h1[1]) + (h1[2] * h1[2] + h1[3] * h1[3]));
;                         u32x4 w; w.x = cvt_pk_bf16(h0[0], h0[1]); w.y = cvt_pk_bf16(h0[2], h0[3]); w.z = cvt_pk_bf16(h1[0], h1[1]); w.w = cvt_pk_bf16(h1[2], h1[3]);
;                         *(u32x4*)(hbp + bj * HALF) = w; } }
;                 if (fin) { { const int ln = fr + 16 * fq; ss += __int_as_float(__builtin_amdgcn_ds_bpermute((ln ^ 16) << 2, __float_as_int(ss))); ss += __int_as_float(__builtin_amdgcn_ds_bpermute((ln ^ 32) << 2, __float_as_int(ss))); }
;                     if (fq == 0) atomicAdd(SSn + row, ss); } }
	v_pk_add_f32 v[114:115], v[114:115], v[180:181]
	v_pk_add_f32 v[116:117], v[116:117], v[182:183]
	v_pk_add_f32 v[110:111], v[110:111], v[188:189]
	v_pk_add_f32 v[112:113], v[112:113], v[190:191]
	v_pk_add_f32 v[106:107], v[106:107], v[192:193]
	v_pk_add_f32 v[108:109], v[108:109], v[194:195]
	v_pk_add_f32 v[102:103], v[102:103], v[196:197]
	v_pk_add_f32 v[104:105], v[104:105], v[198:199]
	global_load_dwordx4 v[180:183], v[154:155], off
	global_load_dwordx4 v[188:191], v[154:155], off offset:16
	global_load_dwordx4 v[192:195], v[154:155], off offset:512
	global_load_dwordx4 v[196:199], v[154:155], off offset:528
	v_lshl_add_u64 v[154:155], v[154:155], 0, s[2:3]
	global_store_dwordx4 v[152:153], v[114:117], off
	global_store_dwordx4 v[152:153], v[110:113], off offset:16
	global_store_dwordx4 v[152:153], v[106:109], off offset:512
	global_store_dwordx4 v[152:153], v[102:105], off offset:528
	v_lshl_add_u64 v[152:153], v[152:153], 0, s[2:3]
	v_mul_f32_e32 v248, v115, v115
	v_mul_f32_e32 v249, v117, v117
	v_fmac_f32_e32 v248, v114, v114
	v_fmac_f32_e32 v249, v116, v116
	v_add_f32_e32 v248, v248, v249
	v_mul_f32_e32 v250, v111, v111
	v_mul_f32_e32 v230, v113, v113
	v_fmac_f32_e32 v250, v110, v110
	v_fmac_f32_e32 v230, v112, v112
	v_add_f32_e32 v250, v250, v230
	v_add_f32_e32 v248, v248, v250
	v_mul_f32_e32 v231, v107, v107
	v_mul_f32_e32 v249, v109, v109
	v_fmac_f32_e32 v231, v106, v106
	v_fmac_f32_e32 v249, v108, v108
	v_add_f32_e32 v231, v231, v249
	v_mul_f32_e32 v250, v103, v103
	v_mul_f32_e32 v230, v105, v105
	v_fmac_f32_e32 v250, v102, v102
	v_fmac_f32_e32 v230, v104, v104
	v_add_f32_e32 v250, v250, v230
	v_add_f32_e32 v231, v231, v250
	v_add_f32_e32 v248, v248, v231
	ds_bpermute_b32 v230, v158, v248
	v_cvt_pk_bf16_f32 v240, v114, v115
	v_cvt_pk_bf16_f32 v241, v116, v117
	v_cvt_pk_bf16_f32 v242, v110, v111
	v_cvt_pk_bf16_f32 v243, v112, v113
	v_cvt_pk_bf16_f32 v244, v106, v107
	v_cvt_pk_bf16_f32 v245, v108, v109
	v_cvt_pk_bf16_f32 v246, v102, v103
	v_cvt_pk_bf16_f32 v247, v104, v105
	global_store_dwordx4 v[162:163], v[240:243], off
	global_store_dwordx4 v[162:163], v[244:247], off offset:256
	s_waitcnt lgkmcnt(0)
	v_add_f32_e32 v248, v248, v230
	ds_bpermute_b32 v230, v159, v248
	v_lshl_add_u64 v[162:163], v[162:163], 0, s[98:99]
	s_waitcnt lgkmcnt(0)
	v_add_f32_e32 v248, v248, v230
	s_and_saveexec_b64 vcc, s[38:39]
	global_atomic_add_f32 v[186:187], v248, off offset:64
	s_mov_b64 exec, vcc
	s_waitcnt vmcnt(26)
	v_pk_add_f32 v[94:95], v[94:95], v[200:201]
	v_pk_add_f32 v[96:97], v[96:97], v[202:203]
	v_pk_add_f32 v[90:91], v[90:91], v[208:209]
	v_pk_add_f32 v[92:93], v[92:93], v[210:211]
	v_pk_add_f32 v[86:87], v[86:87], v[212:213]
	v_pk_add_f32 v[88:89], v[88:89], v[214:215]
	v_pk_add_f32 v[82:83], v[82:83], v[216:217]
	v_pk_add_f32 v[84:85], v[84:85], v[218:219]
	global_load_dwordx4 v[200:203], v[154:155], off
	global_load_dwordx4 v[208:211], v[154:155], off offset:16
	global_load_dwordx4 v[212:215], v[154:155], off offset:512
	global_load_dwordx4 v[216:219], v[154:155], off offset:528
	v_lshl_add_u64 v[154:155], v[154:155], 0, s[2:3]
	global_store_dwordx4 v[152:153], v[94:97], off
	global_store_dwordx4 v[152:153], v[90:93], off offset:16
	global_store_dwordx4 v[152:153], v[86:89], off offset:512
	global_store_dwordx4 v[152:153], v[82:85], off offset:528
	v_lshl_add_u64 v[152:153], v[152:153], 0, s[2:3]
	v_mul_f32_e32 v248, v95, v95
	v_mul_f32_e32 v249, v97, v97
	v_fmac_f32_e32 v248, v94, v94
	v_fmac_f32_e32 v249, v96, v96
	v_add_f32_e32 v248, v248, v249
	v_mul_f32_e32 v250, v91, v91
	v_mul_f32_e32 v230, v93, v93
	v_fmac_f32_e32 v250, v90, v90
	v_fmac_f32_e32 v230, v92, v92
	v_add_f32_e32 v250, v250, v230
	v_add_f32_e32 v248, v248, v250
	v_mul_f32_e32 v231, v87, v87
	v_mul_f32_e32 v249, v89, v89
	v_fmac_f32_e32 v231, v86, v86
	v_fmac_f32_e32 v249, v88, v88
	v_add_f32_e32 v231, v231, v249
	v_mul_f32_e32 v250, v83, v83
	v_mul_f32_e32 v230, v85, v85
	v_fmac_f32_e32 v250, v82, v82
	v_fmac_f32_e32 v230, v84, v84
	v_add_f32_e32 v250, v250, v230
	v_add_f32_e32 v231, v231, v250
	v_add_f32_e32 v248, v248, v231
	ds_bpermute_b32 v230, v158, v248
	v_cvt_pk_bf16_f32 v240, v94, v95
	v_cvt_pk_bf16_f32 v241, v96, v97
	v_cvt_pk_bf16_f32 v242, v90, v91
	v_cvt_pk_bf16_f32 v243, v92, v93
	v_cvt_pk_bf16_f32 v244, v86, v87
	v_cvt_pk_bf16_f32 v245, v88, v89
	v_cvt_pk_bf16_f32 v246, v82, v83
	v_cvt_pk_bf16_f32 v247, v84, v85
	global_store_dwordx4 v[162:163], v[240:243], off
	global_store_dwordx4 v[162:163], v[244:247], off offset:256
	s_waitcnt lgkmcnt(0)
	v_add_f32_e32 v248, v248, v230
	ds_bpermute_b32 v230, v159, v248
	v_lshl_add_u64 v[162:163], v[162:163], 0, s[98:99]
	s_waitcnt lgkmcnt(0)
	v_add_f32_e32 v248, v248, v230
	s_and_saveexec_b64 vcc, s[38:39]
	global_atomic_add_f32 v[186:187], v248, off offset:128
	s_mov_b64 exec, vcc
	s_waitcnt vmcnt(33)
; __device__ __forceinline__ unsigned cvt_pk_bf16(float lo, float hi) { unsigned r; asm volatile("v_cvt_pk_bf16_f32 %0, %1, %2" : "=v"(r) : "v"(lo), "v"(hi)); return r; }
;     __device__ __forceinline__ void operator()(const f32x4 (&acc)[2][2][4][2], const Unit& u, int wr, int wc, int fr, int fq) const {
;     ...
;         for (int ai = 0; ai < 2; ++ai)
; #pragma unroll
;             for (int m = 0; m < 4; ++m) { const int row = u.pm * BM + ai * HALF + wr * 64 + m * 16 + fr; float* rowp = H + (size_t)row * 2048 + col0; bf16_t* hbp = HB + (size_t)row * 2048 + col0;
;                 const float* inp = (u.pm < 128 ? HinP : HinS) + (size_t)row * 2048 + col0;
;                 float ss = 0.f;
; #pragma unroll
;                 for (int bj = 0; bj < 2; ++bj) { const f32x4 h0 = *(const f32x4*)(inp + bj * HALF) + acc[ai][bj][m][0], h1 = *(const f32x4*)(inp + bj * HALF + 4) + acc[ai][bj][m][1];
;                     *(f32x4*)(rowp + bj * HALF) = h0; *(f32x4*)(rowp + bj * HALF + 4) = h1;
;                     if (fin) { ss += ((h0[0] * h0[0] + h0[1] * h0[1]) + (h0[2] * h0[2] + h0[3] * h0[3])) + ((h1[0] * h1[0] + h1[1] * h1[1]) + (h1[2] * h1[2] + h1[3] * h1[3]));
;                         u32x4 w; w.x = cvt_pk_bf16(h0[0], h0[1]); w.y = cvt_pk_bf16(h0[2], h0[3]); w.z = cvt_pk_bf16(h1[0], h1[1]); w.w = cvt_pk_bf16(h1[2], h1[3]);
;                         *(u32x4*)(hbp + bj * HALF) = w; } }
;                 if (fin) { { const int ln = fr + 16 * fq; ss += __int_as_float(__builtin_amdgcn_ds_bpermute((ln ^ 16) << 2, __float_as_int(ss))); ss += __int_as_float(__builtin_amdgcn_ds_bpermute((ln ^ 32) << 2, __float_as_int(ss))); }
;                     if (fq == 0) atomicAdd(SSn + row, ss); } }
	v_pk_add_f32 v[78:79], v[78:79], v[220:221]
	v_pk_add_f32 v[80:81], v[80:81], v[222:223]
	v_pk_add_f32 v[74:75], v[74:75], v[224:225]
	v_pk_add_f32 v[76:77], v[76:77], v[226:227]
	v_pk_add_f32 v[70:71], v[70:71], v[232:233]
	v_pk_add_f32 v[72:73], v[72:73], v[234:235]
	v_pk_add_f32 v[66:67], v[66:67], v[236:237]
	v_pk_add_f32 v[68:69], v[68:69], v[238:239]
	global_load_dwordx4 v[220:223], v[154:155], off
	global_load_dwordx4 v[224:227], v[154:155], off offset:16
	global_load_dwordx4 v[232:235], v[154:155], off offset:512
	global_load_dwordx4 v[236:239], v[154:155], off offset:528
	global_store_dwordx4 v[152:153], v[78:81], off
	global_store_dwordx4 v[152:153], v[74:77], off offset:16
	global_store_dwordx4 v[152:153], v[70:73], off offset:512
	global_store_dwordx4 v[152:153], v[66:69], off offset:528
	v_lshl_add_u64 v[152:153], v[152:153], 0, s[8:9]
	v_mul_f32_e32 v248, v79, v79
	v_mul_f32_e32 v249, v81, v81
	v_fmac_f32_e32 v248, v78, v78
	v_fmac_f32_e32 v249, v80, v80
	v_add_f32_e32 v248, v248, v249
	v_mul_f32_e32 v250, v75, v75
	v_mul_f32_e32 v230, v77, v77
	v_fmac_f32_e32 v250, v74, v74
	v_fmac_f32_e32 v230, v76, v76
	v_add_f32_e32 v250, v250, v230
	v_add_f32_e32 v248, v248, v250
	v_mul_f32_e32 v231, v71, v71
	v_mul_f32_e32 v249, v73, v73
	v_fmac_f32_e32 v231, v70, v70
	v_fmac_f32_e32 v249, v72, v72
	v_add_f32_e32 v231, v231, v249
	v_mul_f32_e32 v250, v67, v67
	v_mul_f32_e32 v230, v69, v69
	v_fmac_f32_e32 v250, v66, v66
	v_fmac_f32_e32 v230, v68, v68
	v_add_f32_e32 v250, v250, v230
	v_add_f32_e32 v231, v231, v250
	v_add_f32_e32 v248, v248, v231
	ds_bpermute_b32 v230, v158, v248
	v_cvt_pk_bf16_f32 v240, v78, v79
	v_cvt_pk_bf16_f32 v241, v80, v81
	v_cvt_pk_bf16_f32 v242, v74, v75
	v_cvt_pk_bf16_f32 v243, v76, v77
	v_cvt_pk_bf16_f32 v244, v70, v71
	v_cvt_pk_bf16_f32 v245, v72, v73
	v_cvt_pk_bf16_f32 v246, v66, v67
	v_cvt_pk_bf16_f32 v247, v68, v69
	global_store_dwordx4 v[162:163], v[240:243], off
	global_store_dwordx4 v[162:163], v[244:247], off offset:256
	s_waitcnt lgkmcnt(0)
	v_add_f32_e32 v248, v248, v230
	ds_bpermute_b32 v230, v159, v248
	v_lshl_add_u64 v[162:163], v[162:163], 0, s[24:25]
	s_waitcnt lgkmcnt(0)
	v_add_f32_e32 v248, v248, v230
	s_and_saveexec_b64 vcc, s[38:39]
	global_atomic_add_f32 v[186:187], v248, off offset:192
	s_mov_b64 exec, vcc
	s_waitcnt vmcnt(40)
	v_pk_add_f32 v[62:63], v[62:63], v[164:165]
	v_pk_add_f32 v[64:65], v[64:65], v[166:167]
	v_pk_add_f32 v[58:59], v[58:59], v[168:169]
	v_pk_add_f32 v[60:61], v[60:61], v[170:171]
	v_pk_add_f32 v[54:55], v[54:55], v[172:173]
	v_pk_add_f32 v[56:57], v[56:57], v[174:175]
	v_pk_add_f32 v[50:51], v[50:51], v[176:177]
	v_pk_add_f32 v[52:53], v[52:53], v[178:179]
	global_store_dwordx4 v[152:153], v[62:65], off
	global_store_dwordx4 v[152:153], v[58:61], off offset:16
	global_store_dwordx4 v[152:153], v[54:57], off offset:512
	global_store_dwordx4 v[152:153], v[50:53], off offset:528
	v_lshl_add_u64 v[152:153], v[152:153], 0, s[2:3]
	v_mul_f32_e32 v248, v63, v63
	v_mul_f32_e32 v249, v65, v65
	v_fmac_f32_e32 v248, v62, v62
	v_fmac_f32_e32 v249, v64, v64
	v_add_f32_e32 v248, v248, v249
	v_mul_f32_e32 v250, v59, v59
	v_mul_f32_e32 v230, v61, v61
	v_fmac_f32_e32 v250, v58, v58
	v_fmac_f32_e32 v230, v60, v60
	v_add_f32_e32 v250, v250, v230
	v_add_f32_e32 v248, v248, v250
	v_mul_f32_e32 v231, v55, v55
	v_mul_f32_e32 v249, v57, v57
	v_fmac_f32_e32 v231, v54, v54
	v_fmac_f32_e32 v249, v56, v56
	v_add_f32_e32 v231, v231, v249
	v_mul_f32_e32 v250, v51, v51
	v_mul_f32_e32 v230, v53, v53
	v_fmac_f32_e32 v250, v50, v50
	v_fmac_f32_e32 v230, v52, v52
	v_add_f32_e32 v250, v250, v230
	v_add_f32_e32 v231, v231, v250
	v_add_f32_e32 v248, v248, v231
	ds_bpermute_b32 v230, v158, v248
	v_cvt_pk_bf16_f32 v240, v62, v63
	v_cvt_pk_bf16_f32 v241, v64, v65
	v_cvt_pk_bf16_f32 v242, v58, v59
	v_cvt_pk_bf16_f32 v243, v60, v61
	v_cvt_pk_bf16_f32 v244, v54, v55
	v_cvt_pk_bf16_f32 v245, v56, v57
	v_cvt_pk_bf16_f32 v246, v50, v51
	v_cvt_pk_bf16_f32 v247, v52, v53
	global_store_dwordx4 v[162:163], v[240:243], off
	global_store_dwordx4 v[162:163], v[244:247], off offset:256
	s_waitcnt lgkmcnt(0)
	v_add_f32_e32 v248, v248, v230
	ds_bpermute_b32 v230, v159, v248
	v_lshl_add_u64 v[162:163], v[162:163], 0, s[98:99]
	s_waitcnt lgkmcnt(0)
	v_add_f32_e32 v248, v248, v230
	s_and_saveexec_b64 vcc, s[38:39]
	global_atomic_add_f32 v[186:187], v248, off offset:512
	s_mov_b64 exec, vcc
	s_waitcnt vmcnt(36)
; __device__ __forceinline__ unsigned cvt_pk_bf16(float lo, float hi) { unsigned r; asm volatile("v_cvt_pk_bf16_f32 %0, %1, %2" : "=v"(r) : "v"(lo), "v"(hi)); return r; }
;     __device__ __forceinline__ void operator()(const f32x4 (&acc)[2][2][4][2], const Unit& u, int wr, int wc, int fr, int fq) const {
;     ...
;         for (int ai = 0; ai < 2; ++ai)
; #pragma unroll
;             for (int m = 0; m < 4; ++m) { const int row = u.pm * BM + ai * HALF + wr * 64 + m * 16 + fr; float* rowp = H + (size_t)row * 2048 + col0; bf16_t* hbp = HB + (size_t)row * 2048 + col0;
;                 const float* inp = (u.pm < 128 ? HinP : HinS) + (size_t)row * 2048 + col0;
;                 float ss = 0.f;
; #pragma unroll
;                 for (int bj = 0; bj < 2; ++bj) { const f32x4 h0 = *(const f32x4*)(inp + bj * HALF) + acc[ai][bj][m][0], h1 = *(const f32x4*)(inp + bj * HALF + 4) + acc[ai][bj][m][1];
;                     *(f32x4*)(rowp + bj * HALF) = h0; *(f32x4*)(rowp + bj * HALF + 4) = h1;
;                     if (fin) { ss += ((h0[0] * h0[0] + h0[1] * h0[1]) + (h0[2] * h0[2] + h0[3] * h0[3])) + ((h1[0] * h1[0] + h1[1] * h1[1]) + (h1[2] * h1[2] + h1[3] * h1[3]));
;                         u32x4 w; w.x = cvt_pk_bf16(h0[0], h0[1]); w.y = cvt_pk_bf16(h0[2], h0[3]); w.z = cvt_pk_bf16(h1[0], h1[1]); w.w = cvt_pk_bf16(h1[2], h1[3]);
;                         *(u32x4*)(hbp + bj * HALF) = w; } }
;                 if (fin) { { const int ln = fr + 16 * fq; ss += __int_as_float(__builtin_amdgcn_ds_bpermute((ln ^ 16) << 2, __float_as_int(ss))); ss += __int_as_float(__builtin_amdgcn_ds_bpermute((ln ^ 32) << 2, __float_as_int(ss))); }
;                     if (fq == 0) atomicAdd(SSn + row, ss); } }
	v_pk_add_f32 v[46:47], v[46:47], v[180:181]
	v_pk_add_f32 v[48:49], v[48:49], v[182:183]
	v_pk_add_f32 v[42:43], v[42:43], v[188:189]
	v_pk_add_f32 v[44:45], v[44:45], v[190:191]
	v_pk_add_f32 v[38:39], v[38:39], v[192:193]
	v_pk_add_f32 v[40:41], v[40:41], v[194:195]
	v_pk_add_f32 v[34:35], v[34:35], v[196:197]
	v_pk_add_f32 v[36:37], v[36:37], v[198:199]
	global_store_dwordx4 v[152:153], v[46:49], off
	global_store_dwordx4 v[152:153], v[42:45], off offset:16
	global_store_dwordx4 v[152:153], v[38:41], off offset:512
	global_store_dwordx4 v[152:153], v[34:37], off offset:528
	v_lshl_add_u64 v[152:153], v[152:153], 0, s[2:3]
	v_mul_f32_e32 v248, v47, v47
	v_mul_f32_e32 v249, v49, v49
	v_fmac_f32_e32 v248, v46, v46
	v_fmac_f32_e32 v249, v48, v48
	v_add_f32_e32 v248, v248, v249
	v_mul_f32_e32 v250, v43, v43
	v_mul_f32_e32 v230, v45, v45
	v_fmac_f32_e32 v250, v42, v42
	v_fmac_f32_e32 v230, v44, v44
	v_add_f32_e32 v250, v250, v230
	v_add_f32_e32 v248, v248, v250
	v_mul_f32_e32 v231, v39, v39
	v_mul_f32_e32 v249, v41, v41
	v_fmac_f32_e32 v231, v38, v38
	v_fmac_f32_e32 v249, v40, v40
	v_add_f32_e32 v231, v231, v249
	v_mul_f32_e32 v250, v35, v35
	v_mul_f32_e32 v230, v37, v37
	v_fmac_f32_e32 v250, v34, v34
	v_fmac_f32_e32 v230, v36, v36
	v_add_f32_e32 v250, v250, v230
	v_add_f32_e32 v231, v231, v250
	v_add_f32_e32 v248, v248, v231
	ds_bpermute_b32 v230, v158, v248
	v_cvt_pk_bf16_f32 v240, v46, v47
	v_cvt_pk_bf16_f32 v241, v48, v49
	v_cvt_pk_bf16_f32 v242, v42, v43
	v_cvt_pk_bf16_f32 v243, v44, v45
	v_cvt_pk_bf16_f32 v244, v38, v39
	v_cvt_pk_bf16_f32 v245, v40, v41
	v_cvt_pk_bf16_f32 v246, v34, v35
	v_cvt_pk_bf16_f32 v247, v36, v37
	global_store_dwordx4 v[162:163], v[240:243], off
	global_store_dwordx4 v[162:163], v[244:247], off offset:256
	s_waitcnt lgkmcnt(0)
	v_add_f32_e32 v248, v248, v230
	ds_bpermute_b32 v230, v159, v248
	v_lshl_add_u64 v[162:163], v[162:163], 0, s[98:99]
	s_waitcnt lgkmcnt(0)
	v_add_f32_e32 v248, v248, v230
	s_and_saveexec_b64 vcc, s[38:39]
	global_atomic_add_f32 v[186:187], v248, off offset:576
	s_mov_b64 exec, vcc
	s_waitcnt vmcnt(32)
	v_pk_add_f32 v[30:31], v[30:31], v[200:201]
	v_pk_add_f32 v[32:33], v[32:33], v[202:203]
	v_pk_add_f32 v[26:27], v[26:27], v[208:209]
	v_pk_add_f32 v[28:29], v[28:29], v[210:211]
	v_pk_add_f32 v[22:23], v[22:23], v[212:213]
	v_pk_add_f32 v[24:25], v[24:25], v[214:215]
	v_pk_add_f32 v[18:19], v[18:19], v[216:217]
	v_pk_add_f32 v[20:21], v[20:21], v[218:219]
	global_store_dwordx4 v[152:153], v[30:33], off
	global_store_dwordx4 v[152:153], v[26:29], off offset:16
	global_store_dwordx4 v[152:153], v[22:25], off offset:512
	global_store_dwordx4 v[152:153], v[18:21], off offset:528
	v_lshl_add_u64 v[152:153], v[152:153], 0, s[2:3]
	v_mul_f32_e32 v248, v31, v31
	v_mul_f32_e32 v249, v33, v33
	v_fmac_f32_e32 v248, v30, v30
	v_fmac_f32_e32 v249, v32, v32
	v_add_f32_e32 v248, v248, v249
	v_mul_f32_e32 v250, v27, v27
	v_mul_f32_e32 v230, v29, v29
	v_fmac_f32_e32 v250, v26, v26
	v_fmac_f32_e32 v230, v28, v28
	v_add_f32_e32 v250, v250, v230
	v_add_f32_e32 v248, v248, v250
	v_mul_f32_e32 v231, v23, v23
	v_mul_f32_e32 v249, v25, v25
	v_fmac_f32_e32 v231, v22, v22
	v_fmac_f32_e32 v249, v24, v24
	v_add_f32_e32 v231, v231, v249
	v_mul_f32_e32 v250, v19, v19
	v_mul_f32_e32 v230, v21, v21
	v_fmac_f32_e32 v250, v18, v18
	v_fmac_f32_e32 v230, v20, v20
	v_add_f32_e32 v250, v250, v230
	v_add_f32_e32 v231, v231, v250
	v_add_f32_e32 v248, v248, v231
	ds_bpermute_b32 v230, v158, v248
	v_cvt_pk_bf16_f32 v240, v30, v31
	v_cvt_pk_bf16_f32 v241, v32, v33
	v_cvt_pk_bf16_f32 v242, v26, v27
	v_cvt_pk_bf16_f32 v243, v28, v29
	v_cvt_pk_bf16_f32 v244, v22, v23
	v_cvt_pk_bf16_f32 v245, v24, v25
	v_cvt_pk_bf16_f32 v246, v18, v19
	v_cvt_pk_bf16_f32 v247, v20, v21
	global_store_dwordx4 v[162:163], v[240:243], off
	global_store_dwordx4 v[162:163], v[244:247], off offset:256
	s_waitcnt lgkmcnt(0)
	v_add_f32_e32 v248, v248, v230
	ds_bpermute_b32 v230, v159, v248
	v_lshl_add_u64 v[162:163], v[162:163], 0, s[98:99]
	s_waitcnt lgkmcnt(0)
	v_add_f32_e32 v248, v248, v230
	s_and_saveexec_b64 vcc, s[38:39]
	global_atomic_add_f32 v[186:187], v248, off offset:640
	s_mov_b64 exec, vcc
	s_waitcnt vmcnt(28)
	v_pk_add_f32 v[14:15], v[14:15], v[220:221]
	v_pk_add_f32 v[16:17], v[16:17], v[222:223]
	v_pk_add_f32 v[10:11], v[10:11], v[224:225]
	v_pk_add_f32 v[12:13], v[12:13], v[226:227]
	v_pk_add_f32 v[6:7], v[6:7], v[232:233]
	v_pk_add_f32 v[8:9], v[8:9], v[234:235]
	v_pk_add_f32 v[2:3], v[2:3], v[236:237]
	v_pk_add_f32 v[4:5], v[4:5], v[238:239]
	global_store_dwordx4 v[152:153], v[14:17], off
	global_store_dwordx4 v[152:153], v[10:13], off offset:16
	global_store_dwordx4 v[152:153], v[6:9], off offset:512
	global_store_dwordx4 v[152:153], v[2:5], off offset:528
	v_mul_f32_e32 v248, v15, v15
	v_mul_f32_e32 v249, v17, v17
	v_fmac_f32_e32 v248, v14, v14
	v_fmac_f32_e32 v249, v16, v16
	v_add_f32_e32 v248, v248, v249
	v_mul_f32_e32 v250, v11, v11
	v_mul_f32_e32 v230, v13, v13
	v_fmac_f32_e32 v250, v10, v10
	v_fmac_f32_e32 v230, v12, v12
	v_add_f32_e32 v250, v250, v230
	v_add_f32_e32 v248, v248, v250
	v_mul_f32_e32 v231, v7, v7
	v_mul_f32_e32 v249, v9, v9
	v_fmac_f32_e32 v231, v6, v6
	v_fmac_f32_e32 v249, v8, v8
	v_add_f32_e32 v231, v231, v249
	v_mul_f32_e32 v250, v3, v3
	v_mul_f32_e32 v230, v5, v5
	v_fmac_f32_e32 v250, v2, v2
	v_fmac_f32_e32 v230, v4, v4
	v_add_f32_e32 v250, v250, v230
	v_add_f32_e32 v231, v231, v250
	v_add_f32_e32 v248, v248, v231
	ds_bpermute_b32 v230, v158, v248
	v_cvt_pk_bf16_f32 v240, v14, v15
	v_cvt_pk_bf16_f32 v241, v16, v17
	v_cvt_pk_bf16_f32 v242, v10, v11
	v_cvt_pk_bf16_f32 v243, v12, v13
	v_cvt_pk_bf16_f32 v244, v6, v7
	v_cvt_pk_bf16_f32 v245, v8, v9
	v_cvt_pk_bf16_f32 v246, v2, v3
	v_cvt_pk_bf16_f32 v247, v4, v5
	global_store_dwordx4 v[162:163], v[240:243], off
	global_store_dwordx4 v[162:163], v[244:247], off offset:256
	s_waitcnt lgkmcnt(0)
	v_add_f32_e32 v248, v248, v230
	ds_bpermute_b32 v230, v159, v248
	s_waitcnt lgkmcnt(0)
	v_add_f32_e32 v248, v248, v230
	s_and_saveexec_b64 vcc, s[38:39]
	global_atomic_add_f32 v[186:187], v248, off offset:704
	s_mov_b64 exec, vcc
	s_branch .Lmy_epi_done

; __global__ void __launch_bounds__(NWAVES * 64, 2) hybrid_fwd(Args A) {
;     ...
;             else if ((s == 2 && EN(3)) || (s == 3 && EN(4)) || (s == 4 && EN(5))) {
;                 const bool split = C.G >= 192; bool go = (s == 4); int k0 = split ? KSPLIT : 0, kl = D - k0, gg = C.G, cc = C.bid, mrows = M; size_t roff = 0;
;                 if (s == 2) { go = phase_mixers(A, C, l, rep ? DUP_UN : 7); k0 = 0; kl = KSPLIT; gg = C.G - 128; cc = C.bid - 128; mrows = MP; }
;                 if (s == 3) { phase_post(A, C, l, split ? 8 : 0); go = split && C.bid < 8 && !rep; k0 = 0; kl = KSPLIT; gg = 8; cc = C.bid; mrows = MS; roff = (size_t)MP * D; }
;                 if (go) { pg8::Gemm g{WS_PTR(const bf16, WS_XN) + roff + k0, WS_PTR(const bf16, WS_WOUTT) + (size_t)l * D * D + k0, mrows, D, kl, D}; pg8::StaticOrder S; S.init(mrows, D, gg, cc);
;                     const bool first = (l == 0) && (s != 4 || !split);
;                     float* Hout = ((rep && s == 4) ? WS_PTR(float, WS_U) : A.out) + roff;
;                     pg8::EpiResN E{Hout, first ? (s == 3 ? A.in[I_XS] : A.in[I_XP]) : Hout, first ? A.in[I_XS] - (size_t)MP * D : Hout, WS_PTR(bf16, WS_HB), WS_PTR(float, WS_SS) + (size_t)(l + 1) * M, s == 4 && !rep};
;                     pg8::gemm_phase<pg8::EpiResN, pg8::StaticOrder, G2_ALIGN, true>(C.lds, g, S, E); }
.LBB0_1256:
	v_readlane_b32 s0, v255, 53
	s_cmp_lg_u32 s0, 4
	s_cbranch_scc1 .Lmy_g2_done
	v_readlane_b32 s0, v255, 61
	s_add_i32 s0, s0, 1
	v_writelane_b32 v255, s0, 61
	s_cmp_eq_u32 s0, 1
	s_cbranch_scc1 .Lmy_g2_passB
	s_cmp_eq_u32 s0, 2
	s_cbranch_scc1 .Lmy_g2_passC
	s_branch .Lmy_g2_done
.Lmy_g2_passB:
	s_mov_b32 s11, 1
	s_mov_b64 s[40:41], 0x4000000
	s_mov_b32 s17, 8
	v_readlane_b32 s30, v253, 0
	v_readlane_b32 s3, v253, 19
	v_readlane_b32 s8, v253, 18
	s_mov_b32 s98, 0x8000
	v_writelane_b32 v255, s98, 63
	s_mov_b64 s[52:53], -1
	s_mov_b64 s[38:39], 0
	s_branch .LBB0_1189
.Lmy_g2_passC:
	s_movk_i32 s11, 0x20
	s_mov_b64 s[40:41], 0x3000000
	v_readlane_b32 s17, v253, 3
	v_readlane_b32 s30, v253, 0
	s_movk_i32 s3, 0x800
	s_mov_b32 s8, 0
	s_mov_b32 s98, 0x6000
	v_writelane_b32 v255, s98, 63
	s_mov_b32 s98, 1
	v_writelane_b32 v255, s98, 62
	s_mov_b64 s[52:53], -1
	s_mov_b64 s[38:39], 0
	s_branch .LBB0_1189
